# norm2 priority variant: wave 0 prio 2 plus waves 5-7 prio 1 (desynchronise the two waves of each SIMD)
# baseline (speedup 1.0000x reference)
.Ln2prio_3:
	s_cmp_lt_u32 s100, 5
	s_cbranch_scc1 .Ln2prio_3b
	s_setprio 1
